# in-proj gate epilogue: sigmoid chains re-emitted stage-interleaved in groups of 8 (no pad nops)
# baseline (speedup 1.0000x reference)
.LBB0_239:
	v_lshl_add_u32 v214, s4, 8, v234
	v_ashrrev_i32_e32 v215, 31, v214
	v_lshl_add_u64 v[130:131], v[214:215], 2, s[66:67]
	v_mov_b32_e32 v0, v244
	v_mov_b32_e32 v132, v245
	v_mov_b32_e32 v133, v246
	v_mov_b32_e32 v134, v247
	v_mov_b32_e32 v135, v248
	v_mov_b32_e32 v136, v249
	v_mov_b32_e32 v137, v250
	s_lshl_b32 s57, s44, 8
	v_mov_b32_e32 v130, v251
	s_add_i32 s6, s44, -8
	v_or_b32_e32 v210, 16, v214
	v_or_b32_e32 v206, 32, v214
	v_or_b32_e32 v202, 48, v214
	v_add_u32_e32 v198, 0x80, v214
	v_add_u32_e32 v194, 0x90, v214
	v_add_u32_e32 v190, 0xa0, v214
	v_add_u32_e32 v174, 0xb0, v214
	v_ashrrev_i32_e32 v211, 31, v210
	v_ashrrev_i32_e32 v207, 31, v206
	v_ashrrev_i32_e32 v203, 31, v202
	v_ashrrev_i32_e32 v199, 31, v198
	v_ashrrev_i32_e32 v195, 31, v194
	v_ashrrev_i32_e32 v191, 31, v190
	v_ashrrev_i32_e32 v175, 31, v174
	s_mov_b64 s[4:5], -1
	s_cmp_lt_u32 s6, 9
	s_waitcnt vmcnt(8) lgkmcnt(0)
	v_fmamk_f32 v0, v0, 0x3a000000, v224
	v_cmp_gt_f32_e32 vcc, s19, v0
	v_mul_f32_e32 v131, 0x4b800000, v0
	s_nop 0
	v_cndmask_b32_e32 v0, v0, v131, vcc
	v_rsq_f32_e32 v0, v0
	s_nop 0
	v_mul_f32_e32 v131, 0x45800000, v0
	v_cndmask_b32_e32 v216, v0, v131, vcc
	v_fmamk_f32 v0, v132, 0x3a000000, v224
	v_cmp_gt_f32_e32 vcc, s19, v0
	v_mul_f32_e32 v131, 0x4b800000, v0
	s_nop 0
	v_cndmask_b32_e32 v0, v0, v131, vcc
	v_rsq_f32_e32 v0, v0
	s_nop 0
	v_mul_f32_e32 v131, 0x45800000, v0
	v_cndmask_b32_e32 v212, v0, v131, vcc
	v_fmamk_f32 v0, v133, 0x3a000000, v224
	v_cmp_gt_f32_e32 vcc, s19, v0
	v_mul_f32_e32 v131, 0x4b800000, v0
	s_nop 0
	v_cndmask_b32_e32 v0, v0, v131, vcc
	v_rsq_f32_e32 v0, v0
	s_nop 0
	v_mul_f32_e32 v131, 0x45800000, v0
	v_cndmask_b32_e32 v208, v0, v131, vcc
	v_fmamk_f32 v0, v134, 0x3a000000, v224
	v_cmp_gt_f32_e32 vcc, s19, v0
	v_mul_f32_e32 v131, 0x4b800000, v0
	s_nop 0
	v_cndmask_b32_e32 v0, v0, v131, vcc
	v_rsq_f32_e32 v0, v0
	s_nop 0
	v_mul_f32_e32 v131, 0x45800000, v0
	v_cndmask_b32_e32 v204, v0, v131, vcc
	v_fmamk_f32 v0, v135, 0x3a000000, v224
	v_cmp_gt_f32_e32 vcc, s19, v0
	v_mul_f32_e32 v131, 0x4b800000, v0
	s_nop 0
	v_cndmask_b32_e32 v0, v0, v131, vcc
	v_rsq_f32_e32 v0, v0
	s_nop 0
	v_mul_f32_e32 v131, 0x45800000, v0
	v_cndmask_b32_e32 v200, v0, v131, vcc
	v_fmamk_f32 v0, v136, 0x3a000000, v224
	v_cmp_gt_f32_e32 vcc, s19, v0
	v_mul_f32_e32 v131, 0x4b800000, v0
	s_nop 0
	v_cndmask_b32_e32 v0, v0, v131, vcc
	v_rsq_f32_e32 v0, v0
	s_nop 0
	v_mul_f32_e32 v131, 0x45800000, v0
	v_cndmask_b32_e32 v196, v0, v131, vcc
	v_fmamk_f32 v0, v137, 0x3a000000, v224
	v_cmp_gt_f32_e32 vcc, s19, v0
	v_mul_f32_e32 v131, 0x4b800000, v0
	s_nop 0
	v_cndmask_b32_e32 v0, v0, v131, vcc
	v_rsq_f32_e32 v0, v0
	s_nop 0
	v_mul_f32_e32 v131, 0x45800000, v0
	v_cndmask_b32_e32 v192, v0, v131, vcc
	v_fmamk_f32 v0, v130, 0x3a000000, v224
	v_cmp_gt_f32_e32 vcc, s19, v0
	v_mul_f32_e32 v130, 0x4b800000, v0
	s_nop 0
	v_cndmask_b32_e32 v0, v0, v130, vcc
	v_rsq_f32_e32 v0, v0
	s_nop 0
	v_mul_f32_e32 v130, 0x45800000, v0
	v_cndmask_b32_e32 v176, v0, v130, vcc
	v_or_b32_e32 v0, s57, v236
	s_cbranch_scc1 .LBB0_306
	s_cmp_gt_i32 s44, 17
	s_cselect_b64 s[4:5], -1, 0
	v_lshlrev_b64 v[138:139], 14, v[214:215]
	v_pk_mul_f32 v[132:133], v[128:129], v[216:217] op_sel_hi:[1,0]
	v_pk_mul_f32 v[130:131], v[126:127], v[216:217] op_sel_hi:[1,0]
	v_pk_mul_f32 v[136:137], v[124:125], v[216:217] op_sel_hi:[1,0]
	v_pk_mul_f32 v[134:135], v[122:123], v[216:217] op_sel_hi:[1,0]
	s_mov_b64 s[6:7], -1
	s_and_b64 vcc, exec, s[4:5]
	v_lshl_add_u64 v[144:145], s[60:61], 0, v[138:139]
	s_cbranch_vccz .LBB0_242
	v_mul_f32_e32 v148, 0xbfb8aa3b, v130
	v_mul_f32_e32 v149, 0xbfb8aa3b, v131
	v_mul_f32_e32 v150, 0xbfb8aa3b, v132
	v_mul_f32_e32 v151, 0xbfb8aa3b, v133
	v_mul_f32_e32 v152, 0xbfb8aa3b, v134
	v_mul_f32_e32 v153, 0xbfb8aa3b, v135
	v_mul_f32_e32 v154, 0xbfb8aa3b, v136
	v_mul_f32_e32 v155, 0xbfb8aa3b, v137
	s_mov_b64 s[6:7], 0
	v_exp_f32_e32 v148, v148
	v_exp_f32_e32 v149, v149
	v_exp_f32_e32 v150, v150
	v_exp_f32_e32 v151, v151
	v_exp_f32_e32 v152, v152
	v_exp_f32_e32 v153, v153
	v_exp_f32_e32 v154, v154
	v_exp_f32_e32 v155, v155
	v_add_f32_e32 v148, 1.0, v148
	v_add_f32_e32 v149, 1.0, v149
	v_add_f32_e32 v150, 1.0, v150
	v_add_f32_e32 v151, 1.0, v151
	v_add_f32_e32 v152, 1.0, v152
	v_add_f32_e32 v153, 1.0, v153
	v_add_f32_e32 v154, 1.0, v154
	v_add_f32_e32 v155, 1.0, v155
	v_rcp_f32_e32 v148, v148
	v_rcp_f32_e32 v149, v149
	v_rcp_f32_e32 v150, v150
	v_rcp_f32_e32 v151, v151
	v_rcp_f32_e32 v152, v152
	v_rcp_f32_e32 v153, v153
	v_rcp_f32_e32 v154, v154
	v_rcp_f32_e32 v155, v155
	s_nop 0
	v_cvt_pk_bf16_f32 v138, v148, v149
	v_cvt_pk_bf16_f32 v139, v150, v151
	v_cvt_pk_bf16_f32 v140, v152, v153
	v_cvt_pk_bf16_f32 v141, v154, v155
	v_lshl_add_u64 v[142:143], v[0:1], 1, v[144:145]
	v_add_co_u32_e32 v142, vcc, 0xffffdc00, v142
	s_nop 1
	v_addc_co_u32_e32 v143, vcc, -1, v143, vcc
	flat_store_dwordx4 v[142:143], v[138:141] nt

.LBB0_244:
	v_mov_b32_e32 v217, v216
	s_nop 0
	v_mov_b32_e32 v134, v216
	v_mov_b32_e32 v135, v216
	v_cndmask_b32_e64 v138, 0, 1, s[4:5]
	v_pk_mul_f32 v[132:133], v[120:121], v[134:135]
	v_pk_mul_f32 v[130:131], v[118:119], v[216:217]
	v_pk_mul_f32 v[136:137], v[116:117], v[134:135]
	v_pk_mul_f32 v[134:135], v[114:115], v[216:217]
	v_cmp_ne_u32_e64 s[40:41], 1, v138
	s_andn2_b64 vcc, exec, s[4:5]
	s_mov_b64 s[4:5], -1
	s_cbranch_vccnz .LBB0_246
	v_mul_f32_e32 v148, 0xbfb8aa3b, v130
	v_mul_f32_e32 v149, 0xbfb8aa3b, v131
	v_mul_f32_e32 v150, 0xbfb8aa3b, v132
	v_mul_f32_e32 v151, 0xbfb8aa3b, v133
	v_mul_f32_e32 v152, 0xbfb8aa3b, v134
	v_mul_f32_e32 v153, 0xbfb8aa3b, v135
	v_mul_f32_e32 v154, 0xbfb8aa3b, v136
	v_mul_f32_e32 v155, 0xbfb8aa3b, v137
	v_lshl_add_u64 v[144:145], v[0:1], 1, v[144:145]
	v_exp_f32_e32 v148, v148
	v_exp_f32_e32 v149, v149
	v_exp_f32_e32 v150, v150
	v_exp_f32_e32 v151, v151
	v_exp_f32_e32 v152, v152
	v_exp_f32_e32 v153, v153
	v_exp_f32_e32 v154, v154
	v_exp_f32_e32 v155, v155
	s_mov_b64 s[4:5], 0
	v_add_f32_e32 v148, 1.0, v148
	v_add_f32_e32 v149, 1.0, v149
	v_add_f32_e32 v150, 1.0, v150
	v_add_f32_e32 v151, 1.0, v151
	v_add_f32_e32 v152, 1.0, v152
	v_add_f32_e32 v153, 1.0, v153
	v_add_f32_e32 v154, 1.0, v154
	v_add_f32_e32 v155, 1.0, v155
	v_add_co_u32_e32 v144, vcc, 0xffffdd00, v144
	v_rcp_f32_e32 v148, v148
	v_rcp_f32_e32 v149, v149
	v_rcp_f32_e32 v150, v150
	v_rcp_f32_e32 v151, v151
	v_rcp_f32_e32 v152, v152
	v_rcp_f32_e32 v153, v153
	v_rcp_f32_e32 v154, v154
	v_rcp_f32_e32 v155, v155
	v_addc_co_u32_e32 v145, vcc, -1, v145, vcc
	s_nop 0
	v_cvt_pk_bf16_f32 v138, v148, v149
	v_cvt_pk_bf16_f32 v139, v150, v151
	v_cvt_pk_bf16_f32 v140, v152, v153
	v_cvt_pk_bf16_f32 v141, v154, v155
	flat_store_dwordx4 v[144:145], v[138:141] nt

.LBB0_248:
	v_lshlrev_b64 v[138:139], 14, v[210:211]
	v_pk_mul_f32 v[132:133], v[112:113], v[212:213] op_sel_hi:[1,0]
	v_pk_mul_f32 v[130:131], v[110:111], v[212:213] op_sel_hi:[1,0]
	v_pk_mul_f32 v[136:137], v[108:109], v[212:213] op_sel_hi:[1,0]
	v_pk_mul_f32 v[134:135], v[106:107], v[212:213] op_sel_hi:[1,0]
	s_mov_b64 s[4:5], -1
	s_and_b64 vcc, exec, s[40:41]
	v_lshl_add_u64 v[144:145], s[60:61], 0, v[138:139]
	s_cbranch_vccnz .LBB0_250
	v_mul_f32_e32 v148, 0xbfb8aa3b, v130
	v_mul_f32_e32 v149, 0xbfb8aa3b, v131
	v_mul_f32_e32 v150, 0xbfb8aa3b, v132
	v_mul_f32_e32 v151, 0xbfb8aa3b, v133
	v_mul_f32_e32 v152, 0xbfb8aa3b, v134
	v_mul_f32_e32 v153, 0xbfb8aa3b, v135
	v_mul_f32_e32 v154, 0xbfb8aa3b, v136
	v_mul_f32_e32 v155, 0xbfb8aa3b, v137
	s_mov_b64 s[4:5], 0
	v_exp_f32_e32 v148, v148
	v_exp_f32_e32 v149, v149
	v_exp_f32_e32 v150, v150
	v_exp_f32_e32 v151, v151
	v_exp_f32_e32 v152, v152
	v_exp_f32_e32 v153, v153
	v_exp_f32_e32 v154, v154
	v_exp_f32_e32 v155, v155
	v_lshl_add_u64 v[146:147], v[0:1], 1, v[144:145]
	v_add_f32_e32 v148, 1.0, v148
	v_add_f32_e32 v149, 1.0, v149
	v_add_f32_e32 v150, 1.0, v150
	v_add_f32_e32 v151, 1.0, v151
	v_add_f32_e32 v152, 1.0, v152
	v_add_f32_e32 v153, 1.0, v153
	v_add_f32_e32 v154, 1.0, v154
	v_add_f32_e32 v155, 1.0, v155
	v_add_co_u32_e32 v146, vcc, 0xffffdc00, v146
	v_rcp_f32_e32 v148, v148
	v_rcp_f32_e32 v149, v149
	v_rcp_f32_e32 v150, v150
	v_rcp_f32_e32 v151, v151
	v_rcp_f32_e32 v152, v152
	v_rcp_f32_e32 v153, v153
	v_rcp_f32_e32 v154, v154
	v_rcp_f32_e32 v155, v155
	s_nop 0
	v_cvt_pk_bf16_f32 v138, v148, v149
	v_cvt_pk_bf16_f32 v139, v150, v151
	v_cvt_pk_bf16_f32 v140, v152, v153
	v_cvt_pk_bf16_f32 v141, v154, v155
	s_nop 1
	v_addc_co_u32_e32 v147, vcc, -1, v147, vcc
	flat_store_dwordx4 v[146:147], v[138:141] nt

.LBB0_252:
	v_mov_b32_e32 v213, v212
	s_nop 0
	v_mov_b32_e32 v134, v212
	v_mov_b32_e32 v135, v212
	v_pk_mul_f32 v[132:133], v[104:105], v[134:135]
	v_pk_mul_f32 v[130:131], v[102:103], v[212:213]
	v_pk_mul_f32 v[136:137], v[100:101], v[134:135]
	v_pk_mul_f32 v[134:135], v[98:99], v[212:213]
	s_and_b64 vcc, exec, s[40:41]
	s_mov_b64 s[4:5], -1
	s_cbranch_vccnz .LBB0_254
	v_mul_f32_e32 v148, 0xbfb8aa3b, v130
	v_mul_f32_e32 v149, 0xbfb8aa3b, v131
	v_mul_f32_e32 v150, 0xbfb8aa3b, v132
	v_mul_f32_e32 v151, 0xbfb8aa3b, v133
	v_mul_f32_e32 v152, 0xbfb8aa3b, v134
	v_mul_f32_e32 v153, 0xbfb8aa3b, v135
	v_mul_f32_e32 v154, 0xbfb8aa3b, v136
	v_mul_f32_e32 v155, 0xbfb8aa3b, v137
	v_lshl_add_u64 v[144:145], v[0:1], 1, v[144:145]
	v_exp_f32_e32 v148, v148
	v_exp_f32_e32 v149, v149
	v_exp_f32_e32 v150, v150
	v_exp_f32_e32 v151, v151
	v_exp_f32_e32 v152, v152
	v_exp_f32_e32 v153, v153
	v_exp_f32_e32 v154, v154
	v_exp_f32_e32 v155, v155
	s_mov_b64 s[4:5], 0
	v_add_f32_e32 v148, 1.0, v148
	v_add_f32_e32 v149, 1.0, v149
	v_add_f32_e32 v150, 1.0, v150
	v_add_f32_e32 v151, 1.0, v151
	v_add_f32_e32 v152, 1.0, v152
	v_add_f32_e32 v153, 1.0, v153
	v_add_f32_e32 v154, 1.0, v154
	v_add_f32_e32 v155, 1.0, v155
	v_add_co_u32_e32 v144, vcc, 0xffffdd00, v144
	v_rcp_f32_e32 v148, v148
	v_rcp_f32_e32 v149, v149
	v_rcp_f32_e32 v150, v150
	v_rcp_f32_e32 v151, v151
	v_rcp_f32_e32 v152, v152
	v_rcp_f32_e32 v153, v153
	v_rcp_f32_e32 v154, v154
	v_rcp_f32_e32 v155, v155
	v_addc_co_u32_e32 v145, vcc, -1, v145, vcc
	s_nop 0
	v_cvt_pk_bf16_f32 v138, v148, v149
	v_cvt_pk_bf16_f32 v139, v150, v151
	v_cvt_pk_bf16_f32 v140, v152, v153
	v_cvt_pk_bf16_f32 v141, v154, v155
	flat_store_dwordx4 v[144:145], v[138:141] nt

.LBB0_256:
	v_lshlrev_b64 v[138:139], 14, v[206:207]
	v_pk_mul_f32 v[132:133], v[96:97], v[208:209] op_sel_hi:[1,0]
	v_pk_mul_f32 v[130:131], v[94:95], v[208:209] op_sel_hi:[1,0]
	v_pk_mul_f32 v[136:137], v[92:93], v[208:209] op_sel_hi:[1,0]
	v_pk_mul_f32 v[134:135], v[90:91], v[208:209] op_sel_hi:[1,0]
	s_mov_b64 s[4:5], -1
	s_and_b64 vcc, exec, s[40:41]
	v_lshl_add_u64 v[144:145], s[60:61], 0, v[138:139]
	s_cbranch_vccnz .LBB0_258
	v_mul_f32_e32 v148, 0xbfb8aa3b, v130
	v_mul_f32_e32 v149, 0xbfb8aa3b, v131
	v_mul_f32_e32 v150, 0xbfb8aa3b, v132
	v_mul_f32_e32 v151, 0xbfb8aa3b, v133
	v_mul_f32_e32 v152, 0xbfb8aa3b, v134
	v_mul_f32_e32 v153, 0xbfb8aa3b, v135
	v_mul_f32_e32 v154, 0xbfb8aa3b, v136
	v_mul_f32_e32 v155, 0xbfb8aa3b, v137
	s_mov_b64 s[4:5], 0
	v_exp_f32_e32 v148, v148
	v_exp_f32_e32 v149, v149
	v_exp_f32_e32 v150, v150
	v_exp_f32_e32 v151, v151
	v_exp_f32_e32 v152, v152
	v_exp_f32_e32 v153, v153
	v_exp_f32_e32 v154, v154
	v_exp_f32_e32 v155, v155
	v_lshl_add_u64 v[146:147], v[0:1], 1, v[144:145]
	v_add_f32_e32 v148, 1.0, v148
	v_add_f32_e32 v149, 1.0, v149
	v_add_f32_e32 v150, 1.0, v150
	v_add_f32_e32 v151, 1.0, v151
	v_add_f32_e32 v152, 1.0, v152
	v_add_f32_e32 v153, 1.0, v153
	v_add_f32_e32 v154, 1.0, v154
	v_add_f32_e32 v155, 1.0, v155
	v_add_co_u32_e32 v146, vcc, 0xffffdc00, v146
	v_rcp_f32_e32 v148, v148
	v_rcp_f32_e32 v149, v149
	v_rcp_f32_e32 v150, v150
	v_rcp_f32_e32 v151, v151
	v_rcp_f32_e32 v152, v152
	v_rcp_f32_e32 v153, v153
	v_rcp_f32_e32 v154, v154
	v_rcp_f32_e32 v155, v155
	s_nop 0
	v_cvt_pk_bf16_f32 v138, v148, v149
	v_cvt_pk_bf16_f32 v139, v150, v151
	v_cvt_pk_bf16_f32 v140, v152, v153
	v_cvt_pk_bf16_f32 v141, v154, v155
	s_nop 1
	v_addc_co_u32_e32 v147, vcc, -1, v147, vcc
	flat_store_dwordx4 v[146:147], v[138:141] nt

.LBB0_260:
	v_mov_b32_e32 v209, v208
	s_nop 0
	v_mov_b32_e32 v134, v208
	v_mov_b32_e32 v135, v208
	v_pk_mul_f32 v[132:133], v[88:89], v[134:135]
	v_pk_mul_f32 v[130:131], v[86:87], v[208:209]
	v_pk_mul_f32 v[136:137], v[84:85], v[134:135]
	v_pk_mul_f32 v[134:135], v[82:83], v[208:209]
	s_and_b64 vcc, exec, s[40:41]
	s_mov_b64 s[4:5], -1
	s_cbranch_vccnz .LBB0_262
	v_mul_f32_e32 v148, 0xbfb8aa3b, v130
	v_mul_f32_e32 v149, 0xbfb8aa3b, v131
	v_mul_f32_e32 v150, 0xbfb8aa3b, v132
	v_mul_f32_e32 v151, 0xbfb8aa3b, v133
	v_mul_f32_e32 v152, 0xbfb8aa3b, v134
	v_mul_f32_e32 v153, 0xbfb8aa3b, v135
	v_mul_f32_e32 v154, 0xbfb8aa3b, v136
	v_mul_f32_e32 v155, 0xbfb8aa3b, v137
	v_lshl_add_u64 v[144:145], v[0:1], 1, v[144:145]
	v_exp_f32_e32 v148, v148
	v_exp_f32_e32 v149, v149
	v_exp_f32_e32 v150, v150
	v_exp_f32_e32 v151, v151
	v_exp_f32_e32 v152, v152
	v_exp_f32_e32 v153, v153
	v_exp_f32_e32 v154, v154
	v_exp_f32_e32 v155, v155
	s_mov_b64 s[4:5], 0
	v_add_f32_e32 v148, 1.0, v148
	v_add_f32_e32 v149, 1.0, v149
	v_add_f32_e32 v150, 1.0, v150
	v_add_f32_e32 v151, 1.0, v151
	v_add_f32_e32 v152, 1.0, v152
	v_add_f32_e32 v153, 1.0, v153
	v_add_f32_e32 v154, 1.0, v154
	v_add_f32_e32 v155, 1.0, v155
	v_add_co_u32_e32 v144, vcc, 0xffffdd00, v144
	v_rcp_f32_e32 v148, v148
	v_rcp_f32_e32 v149, v149
	v_rcp_f32_e32 v150, v150
	v_rcp_f32_e32 v151, v151
	v_rcp_f32_e32 v152, v152
	v_rcp_f32_e32 v153, v153
	v_rcp_f32_e32 v154, v154
	v_rcp_f32_e32 v155, v155
	v_addc_co_u32_e32 v145, vcc, -1, v145, vcc
	s_nop 0
	v_cvt_pk_bf16_f32 v138, v148, v149
	v_cvt_pk_bf16_f32 v139, v150, v151
	v_cvt_pk_bf16_f32 v140, v152, v153
	v_cvt_pk_bf16_f32 v141, v154, v155
	flat_store_dwordx4 v[144:145], v[138:141] nt

.LBB0_264:
	v_lshlrev_b64 v[138:139], 14, v[202:203]
	v_pk_mul_f32 v[132:133], v[80:81], v[204:205] op_sel_hi:[1,0]
	v_pk_mul_f32 v[130:131], v[78:79], v[204:205] op_sel_hi:[1,0]
	v_pk_mul_f32 v[136:137], v[76:77], v[204:205] op_sel_hi:[1,0]
	v_pk_mul_f32 v[134:135], v[74:75], v[204:205] op_sel_hi:[1,0]
	s_mov_b64 s[4:5], -1
	s_and_b64 vcc, exec, s[40:41]
	v_lshl_add_u64 v[144:145], s[60:61], 0, v[138:139]
	s_cbranch_vccnz .LBB0_266
	v_mul_f32_e32 v148, 0xbfb8aa3b, v130
	v_mul_f32_e32 v149, 0xbfb8aa3b, v131
	v_mul_f32_e32 v150, 0xbfb8aa3b, v132
	v_mul_f32_e32 v151, 0xbfb8aa3b, v133
	v_mul_f32_e32 v152, 0xbfb8aa3b, v134
	v_mul_f32_e32 v153, 0xbfb8aa3b, v135
	v_mul_f32_e32 v154, 0xbfb8aa3b, v136
	v_mul_f32_e32 v155, 0xbfb8aa3b, v137
	s_mov_b64 s[4:5], 0
	v_exp_f32_e32 v148, v148
	v_exp_f32_e32 v149, v149
	v_exp_f32_e32 v150, v150
	v_exp_f32_e32 v151, v151
	v_exp_f32_e32 v152, v152
	v_exp_f32_e32 v153, v153
	v_exp_f32_e32 v154, v154
	v_exp_f32_e32 v155, v155
	v_lshl_add_u64 v[146:147], v[0:1], 1, v[144:145]
	v_add_f32_e32 v148, 1.0, v148
	v_add_f32_e32 v149, 1.0, v149
	v_add_f32_e32 v150, 1.0, v150
	v_add_f32_e32 v151, 1.0, v151
	v_add_f32_e32 v152, 1.0, v152
	v_add_f32_e32 v153, 1.0, v153
	v_add_f32_e32 v154, 1.0, v154
	v_add_f32_e32 v155, 1.0, v155
	v_add_co_u32_e32 v146, vcc, 0xffffdc00, v146
	v_rcp_f32_e32 v148, v148
	v_rcp_f32_e32 v149, v149
	v_rcp_f32_e32 v150, v150
	v_rcp_f32_e32 v151, v151
	v_rcp_f32_e32 v152, v152
	v_rcp_f32_e32 v153, v153
	v_rcp_f32_e32 v154, v154
	v_rcp_f32_e32 v155, v155
	s_nop 0
	v_cvt_pk_bf16_f32 v138, v148, v149
	v_cvt_pk_bf16_f32 v139, v150, v151
	v_cvt_pk_bf16_f32 v140, v152, v153
	v_cvt_pk_bf16_f32 v141, v154, v155
	s_nop 1
	v_addc_co_u32_e32 v147, vcc, -1, v147, vcc
	flat_store_dwordx4 v[146:147], v[138:141] nt

.LBB0_268:
	v_mov_b32_e32 v205, v204
	s_nop 0
	v_mov_b32_e32 v134, v204
	v_mov_b32_e32 v135, v204
	v_pk_mul_f32 v[132:133], v[72:73], v[134:135]
	v_pk_mul_f32 v[130:131], v[70:71], v[204:205]
	v_pk_mul_f32 v[136:137], v[68:69], v[134:135]
	v_pk_mul_f32 v[134:135], v[66:67], v[204:205]
	s_and_b64 vcc, exec, s[40:41]
	s_mov_b64 s[4:5], -1
	s_cbranch_vccnz .LBB0_270
	v_mul_f32_e32 v148, 0xbfb8aa3b, v130
	v_mul_f32_e32 v149, 0xbfb8aa3b, v131
	v_mul_f32_e32 v150, 0xbfb8aa3b, v132
	v_mul_f32_e32 v151, 0xbfb8aa3b, v133
	v_mul_f32_e32 v152, 0xbfb8aa3b, v134
	v_mul_f32_e32 v153, 0xbfb8aa3b, v135
	v_mul_f32_e32 v154, 0xbfb8aa3b, v136
	v_mul_f32_e32 v155, 0xbfb8aa3b, v137
	v_lshl_add_u64 v[144:145], v[0:1], 1, v[144:145]
	v_exp_f32_e32 v148, v148
	v_exp_f32_e32 v149, v149
	v_exp_f32_e32 v150, v150
	v_exp_f32_e32 v151, v151
	v_exp_f32_e32 v152, v152
	v_exp_f32_e32 v153, v153
	v_exp_f32_e32 v154, v154
	v_exp_f32_e32 v155, v155
	s_mov_b64 s[4:5], 0
	v_add_f32_e32 v148, 1.0, v148
	v_add_f32_e32 v149, 1.0, v149
	v_add_f32_e32 v150, 1.0, v150
	v_add_f32_e32 v151, 1.0, v151
	v_add_f32_e32 v152, 1.0, v152
	v_add_f32_e32 v153, 1.0, v153
	v_add_f32_e32 v154, 1.0, v154
	v_add_f32_e32 v155, 1.0, v155
	v_add_co_u32_e32 v144, vcc, 0xffffdd00, v144
	v_rcp_f32_e32 v148, v148
	v_rcp_f32_e32 v149, v149
	v_rcp_f32_e32 v150, v150
	v_rcp_f32_e32 v151, v151
	v_rcp_f32_e32 v152, v152
	v_rcp_f32_e32 v153, v153
	v_rcp_f32_e32 v154, v154
	v_rcp_f32_e32 v155, v155
	v_addc_co_u32_e32 v145, vcc, -1, v145, vcc
	s_nop 0
	v_cvt_pk_bf16_f32 v138, v148, v149
	v_cvt_pk_bf16_f32 v139, v150, v151
	v_cvt_pk_bf16_f32 v140, v152, v153
	v_cvt_pk_bf16_f32 v141, v154, v155
	flat_store_dwordx4 v[144:145], v[138:141] nt

.LBB0_272:
	v_lshlrev_b64 v[138:139], 14, v[198:199]
	v_pk_mul_f32 v[132:133], v[64:65], v[200:201] op_sel_hi:[1,0]
	v_pk_mul_f32 v[130:131], v[62:63], v[200:201] op_sel_hi:[1,0]
	v_pk_mul_f32 v[136:137], v[60:61], v[200:201] op_sel_hi:[1,0]
	v_pk_mul_f32 v[134:135], v[58:59], v[200:201] op_sel_hi:[1,0]
	s_mov_b64 s[4:5], -1
	s_and_b64 vcc, exec, s[40:41]
	v_lshl_add_u64 v[144:145], s[60:61], 0, v[138:139]
	s_cbranch_vccnz .LBB0_274
	v_mul_f32_e32 v148, 0xbfb8aa3b, v130
	v_mul_f32_e32 v149, 0xbfb8aa3b, v131
	v_mul_f32_e32 v150, 0xbfb8aa3b, v132
	v_mul_f32_e32 v151, 0xbfb8aa3b, v133
	v_mul_f32_e32 v152, 0xbfb8aa3b, v134
	v_mul_f32_e32 v153, 0xbfb8aa3b, v135
	v_mul_f32_e32 v154, 0xbfb8aa3b, v136
	v_mul_f32_e32 v155, 0xbfb8aa3b, v137
	s_mov_b64 s[4:5], 0
	v_exp_f32_e32 v148, v148
	v_exp_f32_e32 v149, v149
	v_exp_f32_e32 v150, v150
	v_exp_f32_e32 v151, v151
	v_exp_f32_e32 v152, v152
	v_exp_f32_e32 v153, v153
	v_exp_f32_e32 v154, v154
	v_exp_f32_e32 v155, v155
	v_lshl_add_u64 v[146:147], v[0:1], 1, v[144:145]
	v_add_f32_e32 v148, 1.0, v148
	v_add_f32_e32 v149, 1.0, v149
	v_add_f32_e32 v150, 1.0, v150
	v_add_f32_e32 v151, 1.0, v151
	v_add_f32_e32 v152, 1.0, v152
	v_add_f32_e32 v153, 1.0, v153
	v_add_f32_e32 v154, 1.0, v154
	v_add_f32_e32 v155, 1.0, v155
	v_add_co_u32_e32 v146, vcc, 0xffffdc00, v146
	v_rcp_f32_e32 v148, v148
	v_rcp_f32_e32 v149, v149
	v_rcp_f32_e32 v150, v150
	v_rcp_f32_e32 v151, v151
	v_rcp_f32_e32 v152, v152
	v_rcp_f32_e32 v153, v153
	v_rcp_f32_e32 v154, v154
	v_rcp_f32_e32 v155, v155
	s_nop 0
	v_cvt_pk_bf16_f32 v138, v148, v149
	v_cvt_pk_bf16_f32 v139, v150, v151
	v_cvt_pk_bf16_f32 v140, v152, v153
	v_cvt_pk_bf16_f32 v141, v154, v155
	s_nop 1
	v_addc_co_u32_e32 v147, vcc, -1, v147, vcc
	flat_store_dwordx4 v[146:147], v[138:141] nt

.LBB0_276:
	v_mov_b32_e32 v201, v200
	s_nop 0
	v_mov_b32_e32 v134, v200
	v_mov_b32_e32 v135, v200
	v_pk_mul_f32 v[132:133], v[56:57], v[134:135]
	v_pk_mul_f32 v[130:131], v[54:55], v[200:201]
	v_pk_mul_f32 v[136:137], v[52:53], v[134:135]
	v_pk_mul_f32 v[134:135], v[50:51], v[200:201]
	s_and_b64 vcc, exec, s[40:41]
	s_mov_b64 s[4:5], -1
	s_cbranch_vccnz .LBB0_278
	v_mul_f32_e32 v148, 0xbfb8aa3b, v130
	v_mul_f32_e32 v149, 0xbfb8aa3b, v131
	v_mul_f32_e32 v150, 0xbfb8aa3b, v132
	v_mul_f32_e32 v151, 0xbfb8aa3b, v133
	v_mul_f32_e32 v152, 0xbfb8aa3b, v134
	v_mul_f32_e32 v153, 0xbfb8aa3b, v135
	v_mul_f32_e32 v154, 0xbfb8aa3b, v136
	v_mul_f32_e32 v155, 0xbfb8aa3b, v137
	v_lshl_add_u64 v[144:145], v[0:1], 1, v[144:145]
	v_exp_f32_e32 v148, v148
	v_exp_f32_e32 v149, v149
	v_exp_f32_e32 v150, v150
	v_exp_f32_e32 v151, v151
	v_exp_f32_e32 v152, v152
	v_exp_f32_e32 v153, v153
	v_exp_f32_e32 v154, v154
	v_exp_f32_e32 v155, v155
	s_mov_b64 s[4:5], 0
	v_add_f32_e32 v148, 1.0, v148
	v_add_f32_e32 v149, 1.0, v149
	v_add_f32_e32 v150, 1.0, v150
	v_add_f32_e32 v151, 1.0, v151
	v_add_f32_e32 v152, 1.0, v152
	v_add_f32_e32 v153, 1.0, v153
	v_add_f32_e32 v154, 1.0, v154
	v_add_f32_e32 v155, 1.0, v155
	v_add_co_u32_e32 v144, vcc, 0xffffdd00, v144
	v_rcp_f32_e32 v148, v148
	v_rcp_f32_e32 v149, v149
	v_rcp_f32_e32 v150, v150
	v_rcp_f32_e32 v151, v151
	v_rcp_f32_e32 v152, v152
	v_rcp_f32_e32 v153, v153
	v_rcp_f32_e32 v154, v154
	v_rcp_f32_e32 v155, v155
	v_addc_co_u32_e32 v145, vcc, -1, v145, vcc
	s_nop 0
	v_cvt_pk_bf16_f32 v138, v148, v149
	v_cvt_pk_bf16_f32 v139, v150, v151
	v_cvt_pk_bf16_f32 v140, v152, v153
	v_cvt_pk_bf16_f32 v141, v154, v155
	flat_store_dwordx4 v[144:145], v[138:141] nt

.LBB0_280:
	v_lshlrev_b64 v[138:139], 14, v[194:195]
	v_pk_mul_f32 v[132:133], v[48:49], v[196:197] op_sel_hi:[1,0]
	v_pk_mul_f32 v[130:131], v[46:47], v[196:197] op_sel_hi:[1,0]
	v_pk_mul_f32 v[136:137], v[44:45], v[196:197] op_sel_hi:[1,0]
	v_pk_mul_f32 v[134:135], v[42:43], v[196:197] op_sel_hi:[1,0]
	s_mov_b64 s[4:5], -1
	s_and_b64 vcc, exec, s[40:41]
	v_lshl_add_u64 v[144:145], s[60:61], 0, v[138:139]
	s_cbranch_vccnz .LBB0_282
	v_mul_f32_e32 v148, 0xbfb8aa3b, v130
	v_mul_f32_e32 v149, 0xbfb8aa3b, v131
	v_mul_f32_e32 v150, 0xbfb8aa3b, v132
	v_mul_f32_e32 v151, 0xbfb8aa3b, v133
	v_mul_f32_e32 v152, 0xbfb8aa3b, v134
	v_mul_f32_e32 v153, 0xbfb8aa3b, v135
	v_mul_f32_e32 v154, 0xbfb8aa3b, v136
	v_mul_f32_e32 v155, 0xbfb8aa3b, v137
	s_mov_b64 s[4:5], 0
	v_exp_f32_e32 v148, v148
	v_exp_f32_e32 v149, v149
	v_exp_f32_e32 v150, v150
	v_exp_f32_e32 v151, v151
	v_exp_f32_e32 v152, v152
	v_exp_f32_e32 v153, v153
	v_exp_f32_e32 v154, v154
	v_exp_f32_e32 v155, v155
	v_lshl_add_u64 v[146:147], v[0:1], 1, v[144:145]
	v_add_f32_e32 v148, 1.0, v148
	v_add_f32_e32 v149, 1.0, v149
	v_add_f32_e32 v150, 1.0, v150
	v_add_f32_e32 v151, 1.0, v151
	v_add_f32_e32 v152, 1.0, v152
	v_add_f32_e32 v153, 1.0, v153
	v_add_f32_e32 v154, 1.0, v154
	v_add_f32_e32 v155, 1.0, v155
	v_add_co_u32_e32 v146, vcc, 0xffffdc00, v146
	v_rcp_f32_e32 v148, v148
	v_rcp_f32_e32 v149, v149
	v_rcp_f32_e32 v150, v150
	v_rcp_f32_e32 v151, v151
	v_rcp_f32_e32 v152, v152
	v_rcp_f32_e32 v153, v153
	v_rcp_f32_e32 v154, v154
	v_rcp_f32_e32 v155, v155
	s_nop 0
	v_cvt_pk_bf16_f32 v138, v148, v149
	v_cvt_pk_bf16_f32 v139, v150, v151
	v_cvt_pk_bf16_f32 v140, v152, v153
	v_cvt_pk_bf16_f32 v141, v154, v155
	s_nop 1
	v_addc_co_u32_e32 v147, vcc, -1, v147, vcc
	flat_store_dwordx4 v[146:147], v[138:141] nt

.LBB0_284:
	v_mov_b32_e32 v197, v196
	s_nop 0
	v_mov_b32_e32 v134, v196
	v_mov_b32_e32 v135, v196
	v_pk_mul_f32 v[132:133], v[40:41], v[134:135]
	v_pk_mul_f32 v[130:131], v[38:39], v[196:197]
	v_pk_mul_f32 v[136:137], v[36:37], v[134:135]
	v_pk_mul_f32 v[134:135], v[34:35], v[196:197]
	s_and_b64 vcc, exec, s[40:41]
	s_mov_b64 s[4:5], -1
	s_cbranch_vccnz .LBB0_286
	v_mul_f32_e32 v148, 0xbfb8aa3b, v130
	v_mul_f32_e32 v149, 0xbfb8aa3b, v131
	v_mul_f32_e32 v150, 0xbfb8aa3b, v132
	v_mul_f32_e32 v151, 0xbfb8aa3b, v133
	v_mul_f32_e32 v152, 0xbfb8aa3b, v134
	v_mul_f32_e32 v153, 0xbfb8aa3b, v135
	v_mul_f32_e32 v154, 0xbfb8aa3b, v136
	v_mul_f32_e32 v155, 0xbfb8aa3b, v137
	v_lshl_add_u64 v[144:145], v[0:1], 1, v[144:145]
	v_exp_f32_e32 v148, v148
	v_exp_f32_e32 v149, v149
	v_exp_f32_e32 v150, v150
	v_exp_f32_e32 v151, v151
	v_exp_f32_e32 v152, v152
	v_exp_f32_e32 v153, v153
	v_exp_f32_e32 v154, v154
	v_exp_f32_e32 v155, v155
	s_mov_b64 s[4:5], 0
	v_add_f32_e32 v148, 1.0, v148
	v_add_f32_e32 v149, 1.0, v149
	v_add_f32_e32 v150, 1.0, v150
	v_add_f32_e32 v151, 1.0, v151
	v_add_f32_e32 v152, 1.0, v152
	v_add_f32_e32 v153, 1.0, v153
	v_add_f32_e32 v154, 1.0, v154
	v_add_f32_e32 v155, 1.0, v155
	v_add_co_u32_e32 v144, vcc, 0xffffdd00, v144
	v_rcp_f32_e32 v148, v148
	v_rcp_f32_e32 v149, v149
	v_rcp_f32_e32 v150, v150
	v_rcp_f32_e32 v151, v151
	v_rcp_f32_e32 v152, v152
	v_rcp_f32_e32 v153, v153
	v_rcp_f32_e32 v154, v154
	v_rcp_f32_e32 v155, v155
	v_addc_co_u32_e32 v145, vcc, -1, v145, vcc
	s_nop 0
	v_cvt_pk_bf16_f32 v138, v148, v149
	v_cvt_pk_bf16_f32 v139, v150, v151
	v_cvt_pk_bf16_f32 v140, v152, v153
	v_cvt_pk_bf16_f32 v141, v154, v155
	flat_store_dwordx4 v[144:145], v[138:141] nt

.LBB0_288:
	v_lshlrev_b64 v[138:139], 14, v[190:191]
	v_pk_mul_f32 v[132:133], v[32:33], v[192:193] op_sel_hi:[1,0]
	v_pk_mul_f32 v[130:131], v[30:31], v[192:193] op_sel_hi:[1,0]
	v_pk_mul_f32 v[136:137], v[28:29], v[192:193] op_sel_hi:[1,0]
	v_pk_mul_f32 v[134:135], v[26:27], v[192:193] op_sel_hi:[1,0]
	s_mov_b64 s[4:5], -1
	s_and_b64 vcc, exec, s[40:41]
	v_lshl_add_u64 v[144:145], s[60:61], 0, v[138:139]
	s_cbranch_vccnz .LBB0_290
	v_mul_f32_e32 v148, 0xbfb8aa3b, v130
	v_mul_f32_e32 v149, 0xbfb8aa3b, v131
	v_mul_f32_e32 v150, 0xbfb8aa3b, v132
	v_mul_f32_e32 v151, 0xbfb8aa3b, v133
	v_mul_f32_e32 v152, 0xbfb8aa3b, v134
	v_mul_f32_e32 v153, 0xbfb8aa3b, v135
	v_mul_f32_e32 v154, 0xbfb8aa3b, v136
	v_mul_f32_e32 v155, 0xbfb8aa3b, v137
	s_mov_b64 s[4:5], 0
	v_exp_f32_e32 v148, v148
	v_exp_f32_e32 v149, v149
	v_exp_f32_e32 v150, v150
	v_exp_f32_e32 v151, v151
	v_exp_f32_e32 v152, v152
	v_exp_f32_e32 v153, v153
	v_exp_f32_e32 v154, v154
	v_exp_f32_e32 v155, v155
	v_lshl_add_u64 v[146:147], v[0:1], 1, v[144:145]
	v_add_f32_e32 v148, 1.0, v148
	v_add_f32_e32 v149, 1.0, v149
	v_add_f32_e32 v150, 1.0, v150
	v_add_f32_e32 v151, 1.0, v151
	v_add_f32_e32 v152, 1.0, v152
	v_add_f32_e32 v153, 1.0, v153
	v_add_f32_e32 v154, 1.0, v154
	v_add_f32_e32 v155, 1.0, v155
	v_add_co_u32_e32 v146, vcc, 0xffffdc00, v146
	v_rcp_f32_e32 v148, v148
	v_rcp_f32_e32 v149, v149
	v_rcp_f32_e32 v150, v150
	v_rcp_f32_e32 v151, v151
	v_rcp_f32_e32 v152, v152
	v_rcp_f32_e32 v153, v153
	v_rcp_f32_e32 v154, v154
	v_rcp_f32_e32 v155, v155
	s_nop 0
	v_cvt_pk_bf16_f32 v138, v148, v149
	v_cvt_pk_bf16_f32 v139, v150, v151
	v_cvt_pk_bf16_f32 v140, v152, v153
	v_cvt_pk_bf16_f32 v141, v154, v155
	s_nop 1
	v_addc_co_u32_e32 v147, vcc, -1, v147, vcc
	flat_store_dwordx4 v[146:147], v[138:141] nt

.LBB0_292:
	v_mov_b32_e32 v193, v192
	s_nop 0
	v_mov_b32_e32 v134, v192
	v_mov_b32_e32 v135, v192
	v_pk_mul_f32 v[132:133], v[24:25], v[134:135]
	v_pk_mul_f32 v[130:131], v[22:23], v[192:193]
	v_pk_mul_f32 v[136:137], v[20:21], v[134:135]
	v_pk_mul_f32 v[134:135], v[18:19], v[192:193]
	s_and_b64 vcc, exec, s[40:41]
	s_mov_b64 s[4:5], -1
	s_cbranch_vccnz .LBB0_294
	v_mul_f32_e32 v148, 0xbfb8aa3b, v130
	v_mul_f32_e32 v149, 0xbfb8aa3b, v131
	v_mul_f32_e32 v150, 0xbfb8aa3b, v132
	v_mul_f32_e32 v151, 0xbfb8aa3b, v133
	v_mul_f32_e32 v152, 0xbfb8aa3b, v134
	v_mul_f32_e32 v153, 0xbfb8aa3b, v135
	v_mul_f32_e32 v154, 0xbfb8aa3b, v136
	v_mul_f32_e32 v155, 0xbfb8aa3b, v137
	v_lshl_add_u64 v[144:145], v[0:1], 1, v[144:145]
	v_exp_f32_e32 v148, v148
	v_exp_f32_e32 v149, v149
	v_exp_f32_e32 v150, v150
	v_exp_f32_e32 v151, v151
	v_exp_f32_e32 v152, v152
	v_exp_f32_e32 v153, v153
	v_exp_f32_e32 v154, v154
	v_exp_f32_e32 v155, v155
	s_mov_b64 s[4:5], 0
	v_add_f32_e32 v148, 1.0, v148
	v_add_f32_e32 v149, 1.0, v149
	v_add_f32_e32 v150, 1.0, v150
	v_add_f32_e32 v151, 1.0, v151
	v_add_f32_e32 v152, 1.0, v152
	v_add_f32_e32 v153, 1.0, v153
	v_add_f32_e32 v154, 1.0, v154
	v_add_f32_e32 v155, 1.0, v155
	v_add_co_u32_e32 v144, vcc, 0xffffdd00, v144
	v_rcp_f32_e32 v148, v148
	v_rcp_f32_e32 v149, v149
	v_rcp_f32_e32 v150, v150
	v_rcp_f32_e32 v151, v151
	v_rcp_f32_e32 v152, v152
	v_rcp_f32_e32 v153, v153
	v_rcp_f32_e32 v154, v154
	v_rcp_f32_e32 v155, v155
	v_addc_co_u32_e32 v145, vcc, -1, v145, vcc
	s_nop 0
	v_cvt_pk_bf16_f32 v138, v148, v149
	v_cvt_pk_bf16_f32 v139, v150, v151
	v_cvt_pk_bf16_f32 v140, v152, v153
	v_cvt_pk_bf16_f32 v141, v154, v155
	flat_store_dwordx4 v[144:145], v[138:141] nt

.LBB0_296:
	v_lshlrev_b64 v[138:139], 14, v[174:175]
	v_pk_mul_f32 v[132:133], v[16:17], v[176:177] op_sel_hi:[1,0]
	v_pk_mul_f32 v[130:131], v[14:15], v[176:177] op_sel_hi:[1,0]
	v_pk_mul_f32 v[136:137], v[12:13], v[176:177] op_sel_hi:[1,0]
	v_pk_mul_f32 v[134:135], v[10:11], v[176:177] op_sel_hi:[1,0]
	s_mov_b64 s[4:5], -1
	s_and_b64 vcc, exec, s[40:41]
	v_lshl_add_u64 v[144:145], s[60:61], 0, v[138:139]
	s_cbranch_vccnz .LBB0_298
	v_mul_f32_e32 v148, 0xbfb8aa3b, v130
	v_mul_f32_e32 v149, 0xbfb8aa3b, v131
	v_mul_f32_e32 v150, 0xbfb8aa3b, v132
	v_mul_f32_e32 v151, 0xbfb8aa3b, v133
	v_mul_f32_e32 v152, 0xbfb8aa3b, v134
	v_mul_f32_e32 v153, 0xbfb8aa3b, v135
	v_mul_f32_e32 v154, 0xbfb8aa3b, v136
	v_mul_f32_e32 v155, 0xbfb8aa3b, v137
	s_mov_b64 s[4:5], 0
	v_exp_f32_e32 v148, v148
	v_exp_f32_e32 v149, v149
	v_exp_f32_e32 v150, v150
	v_exp_f32_e32 v151, v151
	v_exp_f32_e32 v152, v152
	v_exp_f32_e32 v153, v153
	v_exp_f32_e32 v154, v154
	v_exp_f32_e32 v155, v155
	v_lshl_add_u64 v[146:147], v[0:1], 1, v[144:145]
	v_add_f32_e32 v148, 1.0, v148
	v_add_f32_e32 v149, 1.0, v149
	v_add_f32_e32 v150, 1.0, v150
	v_add_f32_e32 v151, 1.0, v151
	v_add_f32_e32 v152, 1.0, v152
	v_add_f32_e32 v153, 1.0, v153
	v_add_f32_e32 v154, 1.0, v154
	v_add_f32_e32 v155, 1.0, v155
	v_add_co_u32_e32 v146, vcc, 0xffffdc00, v146
	v_rcp_f32_e32 v148, v148
	v_rcp_f32_e32 v149, v149
	v_rcp_f32_e32 v150, v150
	v_rcp_f32_e32 v151, v151
	v_rcp_f32_e32 v152, v152
	v_rcp_f32_e32 v153, v153
	v_rcp_f32_e32 v154, v154
	v_rcp_f32_e32 v155, v155
	s_nop 0
	v_cvt_pk_bf16_f32 v138, v148, v149
	v_cvt_pk_bf16_f32 v139, v150, v151
	v_cvt_pk_bf16_f32 v140, v152, v153
	v_cvt_pk_bf16_f32 v141, v154, v155
	s_nop 1
	v_addc_co_u32_e32 v147, vcc, -1, v147, vcc
	flat_store_dwordx4 v[146:147], v[138:141] nt

.LBB0_300:
	v_mov_b32_e32 v177, v176
	s_nop 0
	v_mov_b32_e32 v134, v176
	v_mov_b32_e32 v135, v176
	v_pk_mul_f32 v[132:133], v[8:9], v[134:135]
	v_pk_mul_f32 v[130:131], v[6:7], v[176:177]
	v_pk_mul_f32 v[136:137], v[4:5], v[134:135]
	v_pk_mul_f32 v[134:135], v[2:3], v[176:177]
	s_and_b64 vcc, exec, s[40:41]
	s_mov_b64 s[4:5], -1
	s_cbranch_vccnz .LBB0_302
	v_mul_f32_e32 v148, 0xbfb8aa3b, v130
	v_mul_f32_e32 v149, 0xbfb8aa3b, v131
	v_mul_f32_e32 v150, 0xbfb8aa3b, v132
	v_mul_f32_e32 v151, 0xbfb8aa3b, v133
	v_mul_f32_e32 v152, 0xbfb8aa3b, v134
	v_mul_f32_e32 v153, 0xbfb8aa3b, v135
	v_mul_f32_e32 v154, 0xbfb8aa3b, v136
	v_mul_f32_e32 v155, 0xbfb8aa3b, v137
	v_lshl_add_u64 v[144:145], v[0:1], 1, v[144:145]
	v_exp_f32_e32 v148, v148
	v_exp_f32_e32 v149, v149
	v_exp_f32_e32 v150, v150
	v_exp_f32_e32 v151, v151
	v_exp_f32_e32 v152, v152
	v_exp_f32_e32 v153, v153
	v_exp_f32_e32 v154, v154
	v_exp_f32_e32 v155, v155
	s_mov_b64 s[4:5], 0
	v_add_f32_e32 v148, 1.0, v148
	v_add_f32_e32 v149, 1.0, v149
	v_add_f32_e32 v150, 1.0, v150
	v_add_f32_e32 v151, 1.0, v151
	v_add_f32_e32 v152, 1.0, v152
	v_add_f32_e32 v153, 1.0, v153
	v_add_f32_e32 v154, 1.0, v154
	v_add_f32_e32 v155, 1.0, v155
	v_add_co_u32_e32 v144, vcc, 0xffffdd00, v144
	v_rcp_f32_e32 v148, v148
	v_rcp_f32_e32 v149, v149
	v_rcp_f32_e32 v150, v150
	v_rcp_f32_e32 v151, v151
	v_rcp_f32_e32 v152, v152
	v_rcp_f32_e32 v153, v153
	v_rcp_f32_e32 v154, v154
	v_rcp_f32_e32 v155, v155
	v_addc_co_u32_e32 v145, vcc, -1, v145, vcc
	s_nop 0
	v_cvt_pk_bf16_f32 v138, v148, v149
	v_cvt_pk_bf16_f32 v139, v150, v151
	v_cvt_pk_bf16_f32 v140, v152, v153
	v_cvt_pk_bf16_f32 v141, v154, v155
	flat_store_dwordx4 v[144:145], v[138:141] nt
